# GEMM-2 epilogue: the residual-stream x loads lose the nt hint (the two waves owning the halves of each 128-byte line now share it in L2); on top of v49
# baseline (speedup 1.0000x reference)
.LBB0_619:
	s_add_i32 s20, s82, -16
	s_lshr_b32 s20, s20, 4
	s_add_i32 s20, s20, 1
	s_cmp_gt_i32 s82, 15
	s_cselect_b64 s[46:47], -1, 0
	s_and_b64 s[24:25], s[46:47], exec
	s_cselect_b32 s20, s20, 0
	s_mul_i32 s24, s20, 9
	s_add_i32 s24, s75, s24
	s_lshl_b32 s24, s24, 10
	s_ashr_i32 s25, s24, 31
	s_lshl_b64 s[24:25], s[24:25], 2
	v_lshl_or_b32 v168, s48, 8, v212
	s_add_u32 s24, s78, s24
	v_ashrrev_i32_e32 v169, 31, v168
	s_addc_u32 s25, s79, s25
	v_lshlrev_b64 v[40:41], 2, v[168:169]
	s_lshl_b32 s20, s20, 10
	v_lshl_add_u64 v[170:171], s[24:25], 0, v[40:41]
	s_lshl_b64 s[24:25], s[20:21], 2
	s_add_u32 s24, s80, s24
	s_addc_u32 s25, s81, s25
	v_lshl_add_u64 v[182:183], s[24:25], 0, v[40:41]
	global_load_dwordx4 v[40:43], v[170:171], off offset:16
	global_load_dwordx4 v[44:47], v[170:171], off
	v_mov_b32_e32 v159, v158
	global_load_dwordx4 v[52:55], v[182:183], off offset:16
	global_load_dwordx4 v[60:63], v[182:183], off
	s_and_b64 vcc, exec, s[28:29]
	s_waitcnt vmcnt(0)
	v_pk_mul_f32 v[174:175], v[158:159], v[42:43]
	v_pk_mul_f32 v[176:177], v[160:161], v[40:41]
	global_load_dwordx4 v[184:187], v[170:171], off offset:528
	global_load_dwordx4 v[40:43], v[170:171], off offset:512
	v_pk_mul_f32 v[178:179], v[158:159], v[46:47]
	v_pk_mul_f32 v[180:181], v[160:161], v[44:45]
	s_waitcnt vmcnt(1)
	v_pk_mul_f32 v[184:185], v[160:161], v[184:185]
	s_waitcnt vmcnt(0)
	v_pk_mul_f32 v[170:171], v[158:159], v[42:43]
	v_pk_mul_f32 v[172:173], v[160:161], v[40:41]
	global_load_dwordx4 v[40:43], v[182:183], off offset:528
	global_load_dwordx4 v[44:47], v[182:183], off offset:512
	v_pk_mul_f32 v[182:183], v[158:159], v[186:187]
	v_lshl_add_u32 v186, s82, 8, v210
	v_ashrrev_i32_e32 v187, 31, v186
	s_cbranch_vccz .LBB0_637
	v_lshlrev_b64 v[188:189], 10, v[186:187]
	v_lshl_add_u64 v[188:189], v[188:189], 0, v[168:169]
	v_lshlrev_b64 v[188:189], 1, v[188:189]
	v_lshl_add_u64 v[190:191], s[14:15], 0, v[188:189]
	global_load_dwordx4 v[214:217], v[190:191], off
	v_lshl_add_u64 v[188:189], s[26:27], 0, v[188:189]
	v_cmp_lt_i32_e32 vcc, v197, v196
	s_lshl_b32 s20, s48, 2
	s_or_b32 s24, s20, s70
	s_ashr_i32 s25, s24, 31
	s_lshl_b64 s[24:25], s[24:25], 2
	s_add_u32 s24, s76, s24
	s_addc_u32 s25, s77, s25
	s_waitcnt vmcnt(0)
	v_lshlrev_b32_e32 v192, 16, v214
	v_and_b32_e32 v193, 0xffff0000, v214
	v_lshlrev_b32_e32 v214, 16, v215
	v_and_b32_e32 v215, 0xffff0000, v215
	v_lshlrev_b32_e32 v218, 16, v216
	v_and_b32_e32 v219, 0xffff0000, v216
	v_lshlrev_b32_e32 v216, 16, v217
	v_and_b32_e32 v217, 0xffff0000, v217
	v_pk_fma_f32 v[220:221], v[142:143], v[178:179], v[214:215]
	v_pk_fma_f32 v[192:193], v[140:141], v[180:181], v[192:193]
	v_pk_fma_f32 v[222:223], v[138:139], v[174:175], v[216:217]
	v_cvt_pk_bf16_f32 v214, v192, v193
	v_pk_fma_f32 v[218:219], v[136:137], v[176:177], v[218:219]
	v_cvt_pk_bf16_f32 v215, v220, v221
	v_cvt_pk_bf16_f32 v217, v222, v223
	v_mul_f32_e32 v159, v193, v193
	v_cvt_pk_bf16_f32 v216, v218, v219
	global_store_dwordx4 v[190:191], v[214:217], off nt
	v_fmac_f32_e32 v159, v192, v192
	v_pk_mul_f32 v[192:193], v[60:61], v[192:193]
	v_mul_f32_e32 v214, v221, v221
	v_fmac_f32_e32 v214, v220, v220
	v_add_f32_e32 v159, v159, v214
	v_mul_f32_e32 v214, v219, v219
	v_mul_f32_e32 v215, v223, v223
	v_fmac_f32_e32 v214, v218, v218
	v_fmac_f32_e32 v215, v222, v222
	v_add_f32_e32 v214, v214, v215
	v_pk_mul_f32 v[216:217], v[62:63], v[220:221]
	v_add_f32_e32 v159, v159, v214
	v_pk_mul_f32 v[220:221], v[54:55], v[222:223]
	v_pk_mul_f32 v[218:219], v[52:53], v[218:219]
	v_cvt_pk_bf16_f32 v214, v192, v193
	v_cvt_pk_bf16_f32 v215, v216, v217
	v_cvt_pk_bf16_f32 v217, v220, v221
	s_nop 0
	v_cvt_pk_bf16_f32 v216, v218, v219
	global_store_dwordx4 v[188:189], v[214:217], off
	global_load_dwordx4 v[214:217], v[190:191], off offset:256
	s_waitcnt vmcnt(0)
	v_lshlrev_b32_e32 v192, 16, v214
	v_and_b32_e32 v193, 0xffff0000, v214
	v_lshlrev_b32_e32 v214, 16, v215
	v_and_b32_e32 v215, 0xffff0000, v215
	v_lshlrev_b32_e32 v218, 16, v216
	v_and_b32_e32 v219, 0xffff0000, v216
	v_lshlrev_b32_e32 v216, 16, v217
	v_and_b32_e32 v217, 0xffff0000, v217
	v_pk_fma_f32 v[220:221], v[134:135], v[170:171], v[214:215]
	v_pk_fma_f32 v[192:193], v[132:133], v[172:173], v[192:193]
	v_pk_fma_f32 v[222:223], v[130:131], v[182:183], v[216:217]
	v_pk_fma_f32 v[218:219], v[128:129], v[184:185], v[218:219]
	v_cvt_pk_bf16_f32 v214, v192, v193
	v_cvt_pk_bf16_f32 v215, v220, v221
	v_cvt_pk_bf16_f32 v217, v222, v223
	s_nop 0
	v_cvt_pk_bf16_f32 v216, v218, v219
	global_store_dwordx4 v[190:191], v[214:217], off offset:256 nt
	v_mul_f32_e32 v190, v193, v193
	v_mul_f32_e32 v191, v221, v221
	v_fmac_f32_e32 v190, v192, v192
	v_fmac_f32_e32 v191, v220, v220
	v_add_f32_e32 v190, v190, v191
	v_mul_f32_e32 v191, v219, v219
	v_mul_f32_e32 v214, v223, v223
	v_fmac_f32_e32 v191, v218, v218
	v_fmac_f32_e32 v214, v222, v222
	v_add_f32_e32 v191, v191, v214
	v_add_f32_e32 v190, v190, v191
	v_add_f32_e32 v224, v159, v190
	v_cndmask_b32_e32 v159, v195, v197, vcc
	v_pk_mul_f32 v[190:191], v[44:45], v[192:193]
	v_pk_mul_f32 v[192:193], v[40:41], v[218:219]
	v_lshlrev_b32_e32 v159, 2, v159
	v_pk_mul_f32 v[214:215], v[46:47], v[220:221]
	v_pk_mul_f32 v[216:217], v[42:43], v[222:223]
	v_cvt_pk_bf16_f32 v190, v190, v191
	v_cvt_pk_bf16_f32 v191, v214, v215
	v_cvt_pk_bf16_f32 v192, v192, v193
	v_cmp_lt_i32_e32 vcc, v198, v196
	v_cvt_pk_bf16_f32 v193, v216, v217
	global_store_dwordx4 v[188:189], v[190:193], off offset:256
	ds_bpermute_b32 v188, v159, v224
	v_cndmask_b32_e32 v189, v195, v198, vcc
	v_lshlrev_b32_e32 v214, 2, v189
	s_waitcnt lgkmcnt(0)
	v_add_f32_e32 v188, v224, v188
	ds_bpermute_b32 v189, v214, v188
	s_and_saveexec_b64 vcc, s[40:41]
	s_cbranch_execz .LBB0_622
	s_waitcnt lgkmcnt(0)
	v_add_f32_e32 v190, v188, v189
	v_lshlrev_b64 v[188:189], 6, v[186:187]
	v_lshl_add_u64 v[188:189], s[24:25], 0, v[188:189]
	global_store_dword v[188:189], v190, off
.LBB0_622:
	s_or_b64 exec, exec, vcc
	v_or_b32_e32 v188, 16, v186
	s_waitcnt lgkmcnt(0)
	v_ashrrev_i32_e32 v189, 31, v188
	v_lshlrev_b64 v[190:191], 10, v[188:189]
	v_lshl_add_u64 v[190:191], v[190:191], 0, v[168:169]
	v_lshlrev_b64 v[190:191], 1, v[190:191]
	v_lshl_add_u64 v[192:193], s[14:15], 0, v[190:191]
	global_load_dwordx4 v[216:219], v[192:193], off
	v_lshl_add_u64 v[190:191], s[26:27], 0, v[190:191]
	s_waitcnt vmcnt(0)
	v_lshlrev_b32_e32 v220, 16, v216
	v_and_b32_e32 v221, 0xffff0000, v216
	v_lshlrev_b32_e32 v216, 16, v217
	v_and_b32_e32 v217, 0xffff0000, v217
	v_lshlrev_b32_e32 v222, 16, v218
	v_and_b32_e32 v223, 0xffff0000, v218
	v_lshlrev_b32_e32 v218, 16, v219
	v_and_b32_e32 v219, 0xffff0000, v219
	v_pk_fma_f32 v[224:225], v[126:127], v[178:179], v[216:217]
	v_pk_fma_f32 v[220:221], v[124:125], v[180:181], v[220:221]
	v_pk_fma_f32 v[226:227], v[122:123], v[174:175], v[218:219]
	v_cvt_pk_bf16_f32 v216, v220, v221
	v_pk_fma_f32 v[222:223], v[120:121], v[176:177], v[222:223]
	v_cvt_pk_bf16_f32 v217, v224, v225
	v_cvt_pk_bf16_f32 v219, v226, v227
	v_mul_f32_e32 v215, v221, v221
	v_cvt_pk_bf16_f32 v218, v222, v223
	global_store_dwordx4 v[192:193], v[216:219], off nt
	v_fmac_f32_e32 v215, v220, v220
	s_nop 0
	v_mul_f32_e32 v216, v225, v225
	v_fmac_f32_e32 v216, v224, v224
	v_add_f32_e32 v215, v215, v216
	v_mul_f32_e32 v216, v223, v223
	v_mul_f32_e32 v217, v227, v227
	v_fmac_f32_e32 v216, v222, v222
	v_fmac_f32_e32 v217, v226, v226
	v_add_f32_e32 v216, v216, v217
	v_add_f32_e32 v215, v215, v216
	v_pk_mul_f32 v[218:219], v[62:63], v[224:225]
	v_pk_mul_f32 v[216:217], v[60:61], v[220:221]
	v_pk_mul_f32 v[220:221], v[54:55], v[226:227]
	v_pk_mul_f32 v[222:223], v[52:53], v[222:223]
	v_cvt_pk_bf16_f32 v216, v216, v217
	v_cvt_pk_bf16_f32 v217, v218, v219
	v_cvt_pk_bf16_f32 v219, v220, v221
	s_nop 0
	v_cvt_pk_bf16_f32 v218, v222, v223
	global_store_dwordx4 v[190:191], v[216:219], off
	global_load_dwordx4 v[216:219], v[192:193], off offset:256
	s_waitcnt vmcnt(0)
	v_lshlrev_b32_e32 v220, 16, v216
	v_and_b32_e32 v221, 0xffff0000, v216
	v_lshlrev_b32_e32 v216, 16, v217
	v_and_b32_e32 v217, 0xffff0000, v217
	v_lshlrev_b32_e32 v222, 16, v218
	v_and_b32_e32 v223, 0xffff0000, v218
	v_lshlrev_b32_e32 v218, 16, v219
	v_and_b32_e32 v219, 0xffff0000, v219
	v_pk_fma_f32 v[224:225], v[118:119], v[170:171], v[216:217]
	v_pk_fma_f32 v[220:221], v[116:117], v[172:173], v[220:221]
	v_pk_fma_f32 v[226:227], v[114:115], v[182:183], v[218:219]
	v_pk_fma_f32 v[222:223], v[112:113], v[184:185], v[222:223]
	v_cvt_pk_bf16_f32 v216, v220, v221
	v_cvt_pk_bf16_f32 v217, v224, v225
	v_cvt_pk_bf16_f32 v219, v226, v227
	s_nop 0
	v_cvt_pk_bf16_f32 v218, v222, v223
	global_store_dwordx4 v[192:193], v[216:219], off offset:256 nt
	v_mul_f32_e32 v192, v221, v221
	v_mul_f32_e32 v193, v225, v225
	v_fmac_f32_e32 v192, v220, v220
	v_fmac_f32_e32 v193, v224, v224
	v_add_f32_e32 v192, v192, v193
	v_mul_f32_e32 v193, v223, v223
	v_mul_f32_e32 v216, v227, v227
	v_fmac_f32_e32 v193, v222, v222
	v_fmac_f32_e32 v216, v226, v226
	v_add_f32_e32 v193, v193, v216
	v_add_f32_e32 v192, v192, v193
	v_add_f32_e32 v215, v215, v192
	v_pk_mul_f32 v[216:217], v[44:45], v[220:221]
	v_pk_mul_f32 v[218:219], v[40:41], v[222:223]
	v_pk_mul_f32 v[192:193], v[46:47], v[224:225]
	v_pk_mul_f32 v[220:221], v[42:43], v[226:227]
	v_cvt_pk_bf16_f32 v216, v216, v217
	v_cvt_pk_bf16_f32 v217, v192, v193
	v_cvt_pk_bf16_f32 v218, v218, v219
	s_nop 0
	v_cvt_pk_bf16_f32 v219, v220, v221
	global_store_dwordx4 v[190:191], v[216:219], off offset:256
	ds_bpermute_b32 v190, v159, v215
	s_waitcnt lgkmcnt(0)
	v_add_f32_e32 v190, v215, v190
	ds_bpermute_b32 v191, v214, v190
	s_and_saveexec_b64 vcc, s[40:41]
	s_cbranch_execz .LBB0_624
	v_lshlrev_b64 v[188:189], 6, v[188:189]
	s_waitcnt lgkmcnt(0)
	v_add_f32_e32 v190, v190, v191
	v_lshl_add_u64 v[188:189], s[24:25], 0, v[188:189]
	global_store_dword v[188:189], v190, off
.LBB0_624:
	s_or_b64 exec, exec, vcc
	v_or_b32_e32 v188, 32, v186
	v_ashrrev_i32_e32 v189, 31, v188
	s_waitcnt lgkmcnt(0)
	v_lshlrev_b64 v[190:191], 10, v[188:189]
	v_lshl_add_u64 v[190:191], v[190:191], 0, v[168:169]
	v_lshlrev_b64 v[190:191], 1, v[190:191]
	v_lshl_add_u64 v[192:193], s[14:15], 0, v[190:191]
	global_load_dwordx4 v[216:219], v[192:193], off
	v_lshl_add_u64 v[190:191], s[26:27], 0, v[190:191]
	s_waitcnt vmcnt(0)
	v_lshlrev_b32_e32 v220, 16, v216
	v_and_b32_e32 v221, 0xffff0000, v216
	v_lshlrev_b32_e32 v216, 16, v217
	v_and_b32_e32 v217, 0xffff0000, v217
	v_lshlrev_b32_e32 v222, 16, v218
	v_and_b32_e32 v223, 0xffff0000, v218
	v_lshlrev_b32_e32 v218, 16, v219
	v_and_b32_e32 v219, 0xffff0000, v219
	v_pk_fma_f32 v[224:225], v[110:111], v[178:179], v[216:217]
	v_pk_fma_f32 v[220:221], v[108:109], v[180:181], v[220:221]
	v_pk_fma_f32 v[226:227], v[106:107], v[174:175], v[218:219]
	v_cvt_pk_bf16_f32 v216, v220, v221
	v_pk_fma_f32 v[222:223], v[104:105], v[176:177], v[222:223]
	v_cvt_pk_bf16_f32 v217, v224, v225
	v_cvt_pk_bf16_f32 v219, v226, v227
	v_mul_f32_e32 v215, v221, v221
	v_cvt_pk_bf16_f32 v218, v222, v223
	global_store_dwordx4 v[192:193], v[216:219], off nt
	v_fmac_f32_e32 v215, v220, v220
	s_nop 0
	v_mul_f32_e32 v216, v225, v225
	v_fmac_f32_e32 v216, v224, v224
	v_add_f32_e32 v215, v215, v216
	v_mul_f32_e32 v216, v223, v223
	v_mul_f32_e32 v217, v227, v227
	v_fmac_f32_e32 v216, v222, v222
	v_fmac_f32_e32 v217, v226, v226
	v_add_f32_e32 v216, v216, v217
	v_add_f32_e32 v215, v215, v216
	v_pk_mul_f32 v[218:219], v[62:63], v[224:225]
	v_pk_mul_f32 v[216:217], v[60:61], v[220:221]
	v_pk_mul_f32 v[220:221], v[54:55], v[226:227]
	v_pk_mul_f32 v[222:223], v[52:53], v[222:223]
	v_cvt_pk_bf16_f32 v216, v216, v217
	v_cvt_pk_bf16_f32 v217, v218, v219
	v_cvt_pk_bf16_f32 v219, v220, v221
	s_nop 0
	v_cvt_pk_bf16_f32 v218, v222, v223
	global_store_dwordx4 v[190:191], v[216:219], off
	global_load_dwordx4 v[216:219], v[192:193], off offset:256
	s_waitcnt vmcnt(0)
	v_lshlrev_b32_e32 v220, 16, v216
	v_and_b32_e32 v221, 0xffff0000, v216
	v_lshlrev_b32_e32 v216, 16, v217
	v_and_b32_e32 v217, 0xffff0000, v217
	v_lshlrev_b32_e32 v222, 16, v218
	v_and_b32_e32 v223, 0xffff0000, v218
	v_lshlrev_b32_e32 v218, 16, v219
	v_and_b32_e32 v219, 0xffff0000, v219
	v_pk_fma_f32 v[224:225], v[102:103], v[170:171], v[216:217]
	v_pk_fma_f32 v[220:221], v[100:101], v[172:173], v[220:221]
	v_pk_fma_f32 v[226:227], v[98:99], v[182:183], v[218:219]
	v_pk_fma_f32 v[222:223], v[96:97], v[184:185], v[222:223]
	v_cvt_pk_bf16_f32 v216, v220, v221
	v_cvt_pk_bf16_f32 v217, v224, v225
	v_cvt_pk_bf16_f32 v219, v226, v227
	s_nop 0
	v_cvt_pk_bf16_f32 v218, v222, v223
	global_store_dwordx4 v[192:193], v[216:219], off offset:256 nt
	v_mul_f32_e32 v192, v221, v221
	v_mul_f32_e32 v193, v225, v225
	v_fmac_f32_e32 v192, v220, v220
	v_fmac_f32_e32 v193, v224, v224
	v_add_f32_e32 v192, v192, v193
	v_mul_f32_e32 v193, v223, v223
	v_mul_f32_e32 v216, v227, v227
	v_fmac_f32_e32 v193, v222, v222
	v_fmac_f32_e32 v216, v226, v226
	v_add_f32_e32 v193, v193, v216
	v_add_f32_e32 v192, v192, v193
	v_add_f32_e32 v215, v215, v192
	v_pk_mul_f32 v[216:217], v[44:45], v[220:221]
	v_pk_mul_f32 v[218:219], v[40:41], v[222:223]
	v_pk_mul_f32 v[192:193], v[46:47], v[224:225]
	v_pk_mul_f32 v[220:221], v[42:43], v[226:227]
	v_cvt_pk_bf16_f32 v216, v216, v217
	v_cvt_pk_bf16_f32 v217, v192, v193
	v_cvt_pk_bf16_f32 v218, v218, v219
	s_nop 0
	v_cvt_pk_bf16_f32 v219, v220, v221
	global_store_dwordx4 v[190:191], v[216:219], off offset:256
	ds_bpermute_b32 v190, v159, v215
	s_waitcnt lgkmcnt(0)
	v_add_f32_e32 v190, v215, v190
	ds_bpermute_b32 v191, v214, v190
	s_and_saveexec_b64 vcc, s[40:41]
	s_cbranch_execz .LBB0_626
	v_lshlrev_b64 v[188:189], 6, v[188:189]
	s_waitcnt lgkmcnt(0)
	v_add_f32_e32 v190, v190, v191
	v_lshl_add_u64 v[188:189], s[24:25], 0, v[188:189]
	global_store_dword v[188:189], v190, off
.LBB0_626:
	s_or_b64 exec, exec, vcc
	v_or_b32_e32 v188, 48, v186
	v_ashrrev_i32_e32 v189, 31, v188
	s_waitcnt lgkmcnt(0)
	v_lshlrev_b64 v[190:191], 10, v[188:189]
	v_lshl_add_u64 v[190:191], v[190:191], 0, v[168:169]
	v_lshlrev_b64 v[190:191], 1, v[190:191]
	v_lshl_add_u64 v[192:193], s[14:15], 0, v[190:191]
	global_load_dwordx4 v[216:219], v[192:193], off
	v_lshl_add_u64 v[190:191], s[26:27], 0, v[190:191]
	s_waitcnt vmcnt(0)
	v_lshlrev_b32_e32 v220, 16, v216
	v_and_b32_e32 v221, 0xffff0000, v216
	v_lshlrev_b32_e32 v216, 16, v217
	v_and_b32_e32 v217, 0xffff0000, v217
	v_lshlrev_b32_e32 v222, 16, v218
	v_and_b32_e32 v223, 0xffff0000, v218
	v_lshlrev_b32_e32 v218, 16, v219
	v_and_b32_e32 v219, 0xffff0000, v219
	v_pk_fma_f32 v[224:225], v[94:95], v[178:179], v[216:217]
	v_pk_fma_f32 v[220:221], v[92:93], v[180:181], v[220:221]
	v_pk_fma_f32 v[226:227], v[90:91], v[174:175], v[218:219]
	v_cvt_pk_bf16_f32 v216, v220, v221
	v_pk_fma_f32 v[222:223], v[88:89], v[176:177], v[222:223]
	v_cvt_pk_bf16_f32 v217, v224, v225
	v_cvt_pk_bf16_f32 v219, v226, v227
	v_mul_f32_e32 v215, v221, v221
	v_cvt_pk_bf16_f32 v218, v222, v223
	global_store_dwordx4 v[192:193], v[216:219], off nt
	v_fmac_f32_e32 v215, v220, v220
	s_nop 0
	v_mul_f32_e32 v216, v225, v225
	v_fmac_f32_e32 v216, v224, v224
	v_add_f32_e32 v215, v215, v216
	v_mul_f32_e32 v216, v223, v223
	v_mul_f32_e32 v217, v227, v227
	v_fmac_f32_e32 v216, v222, v222
	v_fmac_f32_e32 v217, v226, v226
	v_add_f32_e32 v216, v216, v217
	v_add_f32_e32 v215, v215, v216
	v_pk_mul_f32 v[218:219], v[62:63], v[224:225]
	v_pk_mul_f32 v[216:217], v[60:61], v[220:221]
	v_pk_mul_f32 v[220:221], v[54:55], v[226:227]
	v_pk_mul_f32 v[222:223], v[52:53], v[222:223]
	v_cvt_pk_bf16_f32 v216, v216, v217
	v_cvt_pk_bf16_f32 v217, v218, v219
	v_cvt_pk_bf16_f32 v219, v220, v221
	s_nop 0
	v_cvt_pk_bf16_f32 v218, v222, v223
	global_store_dwordx4 v[190:191], v[216:219], off
	global_load_dwordx4 v[216:219], v[192:193], off offset:256
	s_waitcnt vmcnt(0)
	v_lshlrev_b32_e32 v220, 16, v216
	v_and_b32_e32 v221, 0xffff0000, v216
	v_lshlrev_b32_e32 v216, 16, v217
	v_and_b32_e32 v217, 0xffff0000, v217
	v_lshlrev_b32_e32 v222, 16, v218
	v_and_b32_e32 v223, 0xffff0000, v218
	v_lshlrev_b32_e32 v218, 16, v219
	v_and_b32_e32 v219, 0xffff0000, v219
	v_pk_fma_f32 v[224:225], v[86:87], v[170:171], v[216:217]
	v_pk_fma_f32 v[220:221], v[84:85], v[172:173], v[220:221]
	v_pk_fma_f32 v[226:227], v[82:83], v[182:183], v[218:219]
	v_pk_fma_f32 v[222:223], v[80:81], v[184:185], v[222:223]
	v_cvt_pk_bf16_f32 v216, v220, v221
	v_cvt_pk_bf16_f32 v217, v224, v225
	v_cvt_pk_bf16_f32 v219, v226, v227
	s_nop 0
	v_cvt_pk_bf16_f32 v218, v222, v223
	global_store_dwordx4 v[192:193], v[216:219], off offset:256 nt
	v_mul_f32_e32 v192, v221, v221
	v_mul_f32_e32 v193, v225, v225
	v_fmac_f32_e32 v192, v220, v220
	v_fmac_f32_e32 v193, v224, v224
	v_add_f32_e32 v192, v192, v193
	v_mul_f32_e32 v193, v223, v223
	v_mul_f32_e32 v216, v227, v227
	v_fmac_f32_e32 v193, v222, v222
	v_fmac_f32_e32 v216, v226, v226
	v_add_f32_e32 v193, v193, v216
	v_add_f32_e32 v192, v192, v193
	v_add_f32_e32 v215, v215, v192
	v_pk_mul_f32 v[216:217], v[44:45], v[220:221]
	v_pk_mul_f32 v[218:219], v[40:41], v[222:223]
	v_pk_mul_f32 v[192:193], v[46:47], v[224:225]
	v_pk_mul_f32 v[220:221], v[42:43], v[226:227]
	v_cvt_pk_bf16_f32 v216, v216, v217
	v_cvt_pk_bf16_f32 v217, v192, v193
	v_cvt_pk_bf16_f32 v218, v218, v219
	s_nop 0
	v_cvt_pk_bf16_f32 v219, v220, v221
	global_store_dwordx4 v[190:191], v[216:219], off offset:256
	ds_bpermute_b32 v190, v159, v215
	s_waitcnt lgkmcnt(0)
	v_add_f32_e32 v190, v215, v190
	ds_bpermute_b32 v191, v214, v190
	s_and_saveexec_b64 vcc, s[40:41]
	s_cbranch_execz .LBB0_628
	v_lshlrev_b64 v[188:189], 6, v[188:189]
	s_waitcnt lgkmcnt(0)
	v_add_f32_e32 v190, v190, v191
	v_lshl_add_u64 v[188:189], s[24:25], 0, v[188:189]
	global_store_dword v[188:189], v190, off
.LBB0_628:
	s_or_b64 exec, exec, vcc
	v_add_u32_e32 v188, 0x80, v186
	v_ashrrev_i32_e32 v189, 31, v188
	s_waitcnt lgkmcnt(0)
	v_lshlrev_b64 v[190:191], 10, v[188:189]
	v_lshl_add_u64 v[190:191], v[190:191], 0, v[168:169]
	v_lshlrev_b64 v[190:191], 1, v[190:191]
	v_lshl_add_u64 v[192:193], s[14:15], 0, v[190:191]
	global_load_dwordx4 v[216:219], v[192:193], off
	v_lshl_add_u64 v[190:191], s[26:27], 0, v[190:191]
	s_waitcnt vmcnt(0)
	v_lshlrev_b32_e32 v220, 16, v216
	v_and_b32_e32 v221, 0xffff0000, v216
	v_lshlrev_b32_e32 v216, 16, v217
	v_and_b32_e32 v217, 0xffff0000, v217
	v_lshlrev_b32_e32 v222, 16, v218
	v_and_b32_e32 v223, 0xffff0000, v218
	v_lshlrev_b32_e32 v218, 16, v219
	v_and_b32_e32 v219, 0xffff0000, v219
	v_pk_fma_f32 v[224:225], v[78:79], v[178:179], v[216:217]
	v_pk_fma_f32 v[220:221], v[76:77], v[180:181], v[220:221]
	v_pk_fma_f32 v[226:227], v[74:75], v[174:175], v[218:219]
	v_cvt_pk_bf16_f32 v216, v220, v221
	v_pk_fma_f32 v[222:223], v[72:73], v[176:177], v[222:223]
	v_cvt_pk_bf16_f32 v217, v224, v225
	v_cvt_pk_bf16_f32 v219, v226, v227
	v_mul_f32_e32 v215, v221, v221
	v_cvt_pk_bf16_f32 v218, v222, v223
	global_store_dwordx4 v[192:193], v[216:219], off nt
	v_fmac_f32_e32 v215, v220, v220
	s_nop 0
	v_mul_f32_e32 v216, v225, v225
	v_fmac_f32_e32 v216, v224, v224
	v_add_f32_e32 v215, v215, v216
	v_mul_f32_e32 v216, v223, v223
	v_mul_f32_e32 v217, v227, v227
	v_fmac_f32_e32 v216, v222, v222
	v_fmac_f32_e32 v217, v226, v226
	v_add_f32_e32 v216, v216, v217
	v_add_f32_e32 v215, v215, v216
	v_pk_mul_f32 v[218:219], v[62:63], v[224:225]
	v_pk_mul_f32 v[216:217], v[60:61], v[220:221]
	v_pk_mul_f32 v[220:221], v[54:55], v[226:227]
	v_pk_mul_f32 v[222:223], v[52:53], v[222:223]
	v_cvt_pk_bf16_f32 v216, v216, v217
	v_cvt_pk_bf16_f32 v217, v218, v219
	v_cvt_pk_bf16_f32 v219, v220, v221
	s_nop 0
	v_cvt_pk_bf16_f32 v218, v222, v223
	global_store_dwordx4 v[190:191], v[216:219], off
	global_load_dwordx4 v[216:219], v[192:193], off offset:256
	s_waitcnt vmcnt(0)
	v_lshlrev_b32_e32 v220, 16, v216
	v_and_b32_e32 v221, 0xffff0000, v216
	v_lshlrev_b32_e32 v216, 16, v217
	v_and_b32_e32 v217, 0xffff0000, v217
	v_lshlrev_b32_e32 v222, 16, v218
	v_and_b32_e32 v223, 0xffff0000, v218
	v_lshlrev_b32_e32 v218, 16, v219
	v_and_b32_e32 v219, 0xffff0000, v219
	v_pk_fma_f32 v[224:225], v[70:71], v[170:171], v[216:217]
	v_pk_fma_f32 v[220:221], v[68:69], v[172:173], v[220:221]
	v_pk_fma_f32 v[226:227], v[66:67], v[182:183], v[218:219]
	v_pk_fma_f32 v[222:223], v[64:65], v[184:185], v[222:223]
	v_cvt_pk_bf16_f32 v216, v220, v221
	v_cvt_pk_bf16_f32 v217, v224, v225
	v_cvt_pk_bf16_f32 v219, v226, v227
	s_nop 0
	v_cvt_pk_bf16_f32 v218, v222, v223
	global_store_dwordx4 v[192:193], v[216:219], off offset:256 nt
	v_mul_f32_e32 v192, v221, v221
	v_mul_f32_e32 v193, v225, v225
	v_fmac_f32_e32 v192, v220, v220
	v_fmac_f32_e32 v193, v224, v224
	v_add_f32_e32 v192, v192, v193
	v_mul_f32_e32 v193, v223, v223
	v_mul_f32_e32 v216, v227, v227
	v_fmac_f32_e32 v193, v222, v222
	v_fmac_f32_e32 v216, v226, v226
	v_add_f32_e32 v193, v193, v216
	v_add_f32_e32 v192, v192, v193
	v_add_f32_e32 v215, v215, v192
	v_pk_mul_f32 v[216:217], v[44:45], v[220:221]
	v_pk_mul_f32 v[218:219], v[40:41], v[222:223]
	v_pk_mul_f32 v[192:193], v[46:47], v[224:225]
	v_pk_mul_f32 v[220:221], v[42:43], v[226:227]
	v_cvt_pk_bf16_f32 v216, v216, v217
	v_cvt_pk_bf16_f32 v217, v192, v193
	v_cvt_pk_bf16_f32 v218, v218, v219
	s_nop 0
	v_cvt_pk_bf16_f32 v219, v220, v221
	global_store_dwordx4 v[190:191], v[216:219], off offset:256
	ds_bpermute_b32 v190, v159, v215
	s_waitcnt lgkmcnt(0)
	v_add_f32_e32 v190, v215, v190
	ds_bpermute_b32 v191, v214, v190
	s_and_saveexec_b64 vcc, s[40:41]
	s_cbranch_execz .LBB0_630
	v_lshlrev_b64 v[188:189], 6, v[188:189]
	s_waitcnt lgkmcnt(0)
	v_add_f32_e32 v190, v190, v191
	v_lshl_add_u64 v[188:189], s[24:25], 0, v[188:189]
	global_store_dword v[188:189], v190, off
.LBB0_630:
	s_or_b64 exec, exec, vcc
	v_add_u32_e32 v188, 0x90, v186
	v_ashrrev_i32_e32 v189, 31, v188
	s_waitcnt lgkmcnt(0)
	v_lshlrev_b64 v[190:191], 10, v[188:189]
	v_lshl_add_u64 v[190:191], v[190:191], 0, v[168:169]
	v_lshlrev_b64 v[190:191], 1, v[190:191]
	v_lshl_add_u64 v[192:193], s[14:15], 0, v[190:191]
	global_load_dwordx4 v[216:219], v[192:193], off
	v_lshl_add_u64 v[190:191], s[26:27], 0, v[190:191]
	s_waitcnt vmcnt(0)
	v_lshlrev_b32_e32 v220, 16, v216
	v_and_b32_e32 v221, 0xffff0000, v216
	v_lshlrev_b32_e32 v216, 16, v217
	v_and_b32_e32 v217, 0xffff0000, v217
	v_lshlrev_b32_e32 v222, 16, v218
	v_and_b32_e32 v223, 0xffff0000, v218
	v_lshlrev_b32_e32 v218, 16, v219
	v_and_b32_e32 v219, 0xffff0000, v219
	v_pk_fma_f32 v[224:225], v[58:59], v[178:179], v[216:217]
	v_pk_fma_f32 v[220:221], v[56:57], v[180:181], v[220:221]
	v_pk_fma_f32 v[226:227], v[50:51], v[174:175], v[218:219]
	v_cvt_pk_bf16_f32 v216, v220, v221
	v_pk_fma_f32 v[222:223], v[48:49], v[176:177], v[222:223]
	v_cvt_pk_bf16_f32 v217, v224, v225
	v_cvt_pk_bf16_f32 v219, v226, v227
	v_mul_f32_e32 v215, v221, v221
	v_cvt_pk_bf16_f32 v218, v222, v223
	global_store_dwordx4 v[192:193], v[216:219], off nt
	v_fmac_f32_e32 v215, v220, v220
	s_nop 0
	v_mul_f32_e32 v216, v225, v225
	v_fmac_f32_e32 v216, v224, v224
	v_add_f32_e32 v215, v215, v216
	v_mul_f32_e32 v216, v223, v223
	v_mul_f32_e32 v217, v227, v227
	v_fmac_f32_e32 v216, v222, v222
	v_fmac_f32_e32 v217, v226, v226
	v_add_f32_e32 v216, v216, v217
	v_add_f32_e32 v215, v215, v216
	v_pk_mul_f32 v[218:219], v[62:63], v[224:225]
	v_pk_mul_f32 v[216:217], v[60:61], v[220:221]
	v_pk_mul_f32 v[220:221], v[54:55], v[226:227]
	v_pk_mul_f32 v[222:223], v[52:53], v[222:223]
	v_cvt_pk_bf16_f32 v216, v216, v217
	v_cvt_pk_bf16_f32 v217, v218, v219
	v_cvt_pk_bf16_f32 v219, v220, v221
	s_nop 0
	v_cvt_pk_bf16_f32 v218, v222, v223
	global_store_dwordx4 v[190:191], v[216:219], off
	global_load_dwordx4 v[216:219], v[192:193], off offset:256
	s_waitcnt vmcnt(0)
	v_lshlrev_b32_e32 v220, 16, v216
	v_and_b32_e32 v221, 0xffff0000, v216
	v_lshlrev_b32_e32 v216, 16, v217
	v_and_b32_e32 v217, 0xffff0000, v217
	v_lshlrev_b32_e32 v222, 16, v218
	v_and_b32_e32 v223, 0xffff0000, v218
	v_lshlrev_b32_e32 v218, 16, v219
	v_and_b32_e32 v219, 0xffff0000, v219
	v_pk_fma_f32 v[224:225], v[38:39], v[170:171], v[216:217]
	v_pk_fma_f32 v[220:221], v[36:37], v[172:173], v[220:221]
	v_pk_fma_f32 v[226:227], v[34:35], v[182:183], v[218:219]
	v_pk_fma_f32 v[222:223], v[32:33], v[184:185], v[222:223]
	v_cvt_pk_bf16_f32 v216, v220, v221
	v_cvt_pk_bf16_f32 v217, v224, v225
	v_cvt_pk_bf16_f32 v219, v226, v227
	s_nop 0
	v_cvt_pk_bf16_f32 v218, v222, v223
	global_store_dwordx4 v[192:193], v[216:219], off offset:256 nt
	v_mul_f32_e32 v192, v221, v221
	v_mul_f32_e32 v193, v225, v225
	v_fmac_f32_e32 v192, v220, v220
	v_fmac_f32_e32 v193, v224, v224
	v_add_f32_e32 v192, v192, v193
	v_mul_f32_e32 v193, v223, v223
	v_mul_f32_e32 v216, v227, v227
	v_fmac_f32_e32 v193, v222, v222
	v_fmac_f32_e32 v216, v226, v226
	v_add_f32_e32 v193, v193, v216
	v_add_f32_e32 v192, v192, v193
	v_add_f32_e32 v215, v215, v192
	v_pk_mul_f32 v[216:217], v[44:45], v[220:221]
	v_pk_mul_f32 v[218:219], v[40:41], v[222:223]
	v_pk_mul_f32 v[192:193], v[46:47], v[224:225]
	v_pk_mul_f32 v[220:221], v[42:43], v[226:227]
	v_cvt_pk_bf16_f32 v216, v216, v217
	v_cvt_pk_bf16_f32 v217, v192, v193
	v_cvt_pk_bf16_f32 v218, v218, v219
	s_nop 0
	v_cvt_pk_bf16_f32 v219, v220, v221
	global_store_dwordx4 v[190:191], v[216:219], off offset:256
	ds_bpermute_b32 v190, v159, v215
	s_waitcnt lgkmcnt(0)
	v_add_f32_e32 v190, v215, v190
	ds_bpermute_b32 v191, v214, v190
	s_and_saveexec_b64 vcc, s[40:41]
	s_cbranch_execz .LBB0_632
	v_lshlrev_b64 v[188:189], 6, v[188:189]
	s_waitcnt lgkmcnt(0)
	v_add_f32_e32 v190, v190, v191
	v_lshl_add_u64 v[188:189], s[24:25], 0, v[188:189]
	global_store_dword v[188:189], v190, off
.LBB0_632:
	s_or_b64 exec, exec, vcc
	v_add_u32_e32 v188, 0xa0, v186
	v_ashrrev_i32_e32 v189, 31, v188
	s_waitcnt lgkmcnt(0)
	v_lshlrev_b64 v[190:191], 10, v[188:189]
	v_lshl_add_u64 v[190:191], v[190:191], 0, v[168:169]
	v_lshlrev_b64 v[190:191], 1, v[190:191]
	v_lshl_add_u64 v[192:193], s[14:15], 0, v[190:191]
	global_load_dwordx4 v[216:219], v[192:193], off
	v_lshl_add_u64 v[190:191], s[26:27], 0, v[190:191]
	s_waitcnt vmcnt(0)
	v_lshlrev_b32_e32 v220, 16, v216
	v_and_b32_e32 v221, 0xffff0000, v216
	v_lshlrev_b32_e32 v216, 16, v217
	v_and_b32_e32 v217, 0xffff0000, v217
	v_lshlrev_b32_e32 v222, 16, v218
	v_and_b32_e32 v223, 0xffff0000, v218
	v_lshlrev_b32_e32 v218, 16, v219
	v_and_b32_e32 v219, 0xffff0000, v219
	v_pk_fma_f32 v[224:225], v[30:31], v[178:179], v[216:217]
	v_pk_fma_f32 v[220:221], v[28:29], v[180:181], v[220:221]
	v_pk_fma_f32 v[226:227], v[26:27], v[174:175], v[218:219]
	v_cvt_pk_bf16_f32 v216, v220, v221
	v_pk_fma_f32 v[222:223], v[24:25], v[176:177], v[222:223]
	v_cvt_pk_bf16_f32 v217, v224, v225
	v_cvt_pk_bf16_f32 v219, v226, v227
	v_mul_f32_e32 v215, v221, v221
	v_cvt_pk_bf16_f32 v218, v222, v223
	global_store_dwordx4 v[192:193], v[216:219], off nt
	v_fmac_f32_e32 v215, v220, v220
	s_nop 0
	v_mul_f32_e32 v216, v225, v225
	v_fmac_f32_e32 v216, v224, v224
	v_add_f32_e32 v215, v215, v216
	v_mul_f32_e32 v216, v223, v223
	v_mul_f32_e32 v217, v227, v227
	v_fmac_f32_e32 v216, v222, v222
	v_fmac_f32_e32 v217, v226, v226
	v_add_f32_e32 v216, v216, v217
	v_add_f32_e32 v215, v215, v216
	v_pk_mul_f32 v[218:219], v[62:63], v[224:225]
	v_pk_mul_f32 v[216:217], v[60:61], v[220:221]
	v_pk_mul_f32 v[220:221], v[54:55], v[226:227]
	v_pk_mul_f32 v[222:223], v[52:53], v[222:223]
	v_cvt_pk_bf16_f32 v216, v216, v217
	v_cvt_pk_bf16_f32 v217, v218, v219
	v_cvt_pk_bf16_f32 v219, v220, v221
	s_nop 0
	v_cvt_pk_bf16_f32 v218, v222, v223
	global_store_dwordx4 v[190:191], v[216:219], off
	global_load_dwordx4 v[216:219], v[192:193], off offset:256
	s_waitcnt vmcnt(0)
	v_lshlrev_b32_e32 v220, 16, v216
	v_and_b32_e32 v221, 0xffff0000, v216
	v_lshlrev_b32_e32 v216, 16, v217
	v_and_b32_e32 v217, 0xffff0000, v217
	v_lshlrev_b32_e32 v222, 16, v218
	v_and_b32_e32 v223, 0xffff0000, v218
	v_lshlrev_b32_e32 v218, 16, v219
	v_and_b32_e32 v219, 0xffff0000, v219
	v_pk_fma_f32 v[224:225], v[22:23], v[170:171], v[216:217]
	v_pk_fma_f32 v[220:221], v[20:21], v[172:173], v[220:221]
	v_pk_fma_f32 v[226:227], v[18:19], v[182:183], v[218:219]
	v_pk_fma_f32 v[222:223], v[16:17], v[184:185], v[222:223]
	v_cvt_pk_bf16_f32 v216, v220, v221
	v_cvt_pk_bf16_f32 v217, v224, v225
	v_cvt_pk_bf16_f32 v219, v226, v227
	s_nop 0
	v_cvt_pk_bf16_f32 v218, v222, v223
	global_store_dwordx4 v[192:193], v[216:219], off offset:256 nt
	v_mul_f32_e32 v192, v221, v221
	v_mul_f32_e32 v193, v225, v225
	v_fmac_f32_e32 v192, v220, v220
	v_fmac_f32_e32 v193, v224, v224
	v_add_f32_e32 v192, v192, v193
	v_mul_f32_e32 v193, v223, v223
	v_mul_f32_e32 v216, v227, v227
	v_fmac_f32_e32 v193, v222, v222
	v_fmac_f32_e32 v216, v226, v226
	v_add_f32_e32 v193, v193, v216
	v_add_f32_e32 v192, v192, v193
	v_add_f32_e32 v215, v215, v192
	v_pk_mul_f32 v[216:217], v[44:45], v[220:221]
	v_pk_mul_f32 v[218:219], v[40:41], v[222:223]
	v_pk_mul_f32 v[192:193], v[46:47], v[224:225]
	v_pk_mul_f32 v[220:221], v[42:43], v[226:227]
	v_cvt_pk_bf16_f32 v216, v216, v217
	v_cvt_pk_bf16_f32 v217, v192, v193
	v_cvt_pk_bf16_f32 v218, v218, v219
	s_nop 0
	v_cvt_pk_bf16_f32 v219, v220, v221
	global_store_dwordx4 v[190:191], v[216:219], off offset:256
	ds_bpermute_b32 v190, v159, v215
	s_waitcnt lgkmcnt(0)
	v_add_f32_e32 v190, v215, v190
	ds_bpermute_b32 v191, v214, v190
	s_and_saveexec_b64 vcc, s[40:41]
	s_cbranch_execz .LBB0_634
	v_lshlrev_b64 v[188:189], 6, v[188:189]
	s_waitcnt lgkmcnt(0)
	v_add_f32_e32 v190, v190, v191
	v_lshl_add_u64 v[188:189], s[24:25], 0, v[188:189]
	global_store_dword v[188:189], v190, off
.LBB0_634:
	s_or_b64 exec, exec, vcc
	v_add_u32_e32 v188, 0xb0, v186
	v_ashrrev_i32_e32 v189, 31, v188
	s_waitcnt lgkmcnt(0)
	v_lshlrev_b64 v[190:191], 10, v[188:189]
	v_lshl_add_u64 v[190:191], v[190:191], 0, v[168:169]
	v_lshlrev_b64 v[190:191], 1, v[190:191]
	v_lshl_add_u64 v[192:193], s[14:15], 0, v[190:191]
	global_load_dwordx4 v[216:219], v[192:193], off
	v_lshl_add_u64 v[190:191], s[26:27], 0, v[190:191]
	s_waitcnt vmcnt(0)
	v_lshlrev_b32_e32 v220, 16, v216
	v_and_b32_e32 v221, 0xffff0000, v216
	v_lshlrev_b32_e32 v216, 16, v217
	v_and_b32_e32 v217, 0xffff0000, v217
	v_lshlrev_b32_e32 v222, 16, v218
	v_and_b32_e32 v223, 0xffff0000, v218
	v_lshlrev_b32_e32 v218, 16, v219
	v_and_b32_e32 v219, 0xffff0000, v219
	v_pk_fma_f32 v[224:225], v[14:15], v[178:179], v[216:217]
	v_pk_fma_f32 v[220:221], v[12:13], v[180:181], v[220:221]
	v_pk_fma_f32 v[226:227], v[10:11], v[174:175], v[218:219]
	v_cvt_pk_bf16_f32 v216, v220, v221
	v_pk_fma_f32 v[222:223], v[8:9], v[176:177], v[222:223]
	v_cvt_pk_bf16_f32 v217, v224, v225
	v_cvt_pk_bf16_f32 v219, v226, v227
	v_mul_f32_e32 v215, v221, v221
	v_cvt_pk_bf16_f32 v218, v222, v223
	global_store_dwordx4 v[192:193], v[216:219], off nt
	v_fmac_f32_e32 v215, v220, v220
	s_nop 0
	v_mul_f32_e32 v216, v225, v225
	v_fmac_f32_e32 v216, v224, v224
	v_add_f32_e32 v215, v215, v216
	v_mul_f32_e32 v216, v223, v223
	v_mul_f32_e32 v217, v227, v227
	v_fmac_f32_e32 v216, v222, v222
	v_fmac_f32_e32 v217, v226, v226
	v_add_f32_e32 v216, v216, v217
	v_add_f32_e32 v215, v215, v216
	v_pk_mul_f32 v[218:219], v[62:63], v[224:225]
	v_pk_mul_f32 v[216:217], v[60:61], v[220:221]
	v_pk_mul_f32 v[220:221], v[54:55], v[226:227]
	v_pk_mul_f32 v[222:223], v[52:53], v[222:223]
	v_cvt_pk_bf16_f32 v216, v216, v217
	v_cvt_pk_bf16_f32 v217, v218, v219
	v_cvt_pk_bf16_f32 v219, v220, v221
	s_nop 0
	v_cvt_pk_bf16_f32 v218, v222, v223
	global_store_dwordx4 v[190:191], v[216:219], off
	global_load_dwordx4 v[216:219], v[192:193], off offset:256
	s_waitcnt vmcnt(0)
	v_lshlrev_b32_e32 v220, 16, v216
	v_and_b32_e32 v221, 0xffff0000, v216
	v_lshlrev_b32_e32 v216, 16, v217
	v_and_b32_e32 v217, 0xffff0000, v217
	v_lshlrev_b32_e32 v222, 16, v218
	v_and_b32_e32 v223, 0xffff0000, v218
	v_lshlrev_b32_e32 v218, 16, v219
	v_and_b32_e32 v219, 0xffff0000, v219
	v_pk_fma_f32 v[224:225], v[6:7], v[170:171], v[216:217]
	v_pk_fma_f32 v[220:221], v[4:5], v[172:173], v[220:221]
	v_pk_fma_f32 v[226:227], v[2:3], v[182:183], v[218:219]
	v_pk_fma_f32 v[222:223], v[0:1], v[184:185], v[222:223]
	v_cvt_pk_bf16_f32 v216, v220, v221
	v_cvt_pk_bf16_f32 v217, v224, v225
	v_cvt_pk_bf16_f32 v219, v226, v227
	s_nop 0
	v_cvt_pk_bf16_f32 v218, v222, v223
	global_store_dwordx4 v[192:193], v[216:219], off offset:256 nt
	v_mul_f32_e32 v192, v221, v221
	v_mul_f32_e32 v193, v225, v225
	v_fmac_f32_e32 v192, v220, v220
	v_fmac_f32_e32 v193, v224, v224
	v_add_f32_e32 v192, v192, v193
	v_mul_f32_e32 v193, v223, v223
	v_mul_f32_e32 v216, v227, v227
	v_fmac_f32_e32 v193, v222, v222
	v_fmac_f32_e32 v216, v226, v226
	v_add_f32_e32 v193, v193, v216
	v_add_f32_e32 v192, v192, v193
	v_add_f32_e32 v215, v215, v192
	ds_bpermute_b32 v159, v159, v215
	v_pk_mul_f32 v[216:217], v[44:45], v[220:221]
	v_pk_mul_f32 v[218:219], v[40:41], v[222:223]
	v_pk_mul_f32 v[192:193], v[46:47], v[224:225]
	v_pk_mul_f32 v[220:221], v[42:43], v[226:227]
	s_waitcnt lgkmcnt(0)
	v_add_f32_e32 v159, v215, v159
	v_cvt_pk_bf16_f32 v216, v216, v217
	v_cvt_pk_bf16_f32 v217, v192, v193
	v_cvt_pk_bf16_f32 v218, v218, v219
	v_cvt_pk_bf16_f32 v219, v220, v221
	global_store_dwordx4 v[190:191], v[216:219], off offset:256
	ds_bpermute_b32 v190, v214, v159
	s_and_saveexec_b64 vcc, s[40:41]
	s_cbranch_execz .LBB0_636
	v_lshlrev_b64 v[188:189], 6, v[188:189]
	s_waitcnt lgkmcnt(0)
	v_add_f32_e32 v159, v159, v190
	v_lshl_add_u64 v[188:189], s[24:25], 0, v[188:189]
	global_store_dword v[188:189], v159, off
